# lru_local sc loop: next sub-chunk x loads land in final registers, wait+convert deferred past the gate GEMMs/scan
# baseline (speedup 1.0000x reference)
.LBB0_315:
	v_fma_f32 v64, v134, v139, v138
	v_fmac_f32_e32 v64, v135, v69
	v_fmac_f32_e32 v64, v136, v68
	v_fmac_f32_e32 v64, v137, v109
	v_cvt_pk_bf16_f32 v65, v64, s0
	ds_write_b16 v163, v65 offset:32768
	v_fma_f32 v65, v134, v69, v138
	v_fmac_f32_e32 v65, v135, v68
	v_fmac_f32_e32 v65, v136, v109
	v_fmac_f32_e32 v65, v137, v108
	ds_write2st64_b32 v145, v64, v65 offset1:8
	v_cvt_pk_bf16_f32 v64, v65, s0
	ds_write_b16 v163, v64 offset:33808
	v_fma_f32 v64, v134, v68, v138
	v_fmac_f32_e32 v64, v135, v109
	v_fmac_f32_e32 v64, v136, v108
	v_fmac_f32_e32 v64, v137, v111
	v_cvt_pk_bf16_f32 v65, v64, s0
	ds_write_b16 v163, v65 offset:34848
	v_fma_f32 v65, v134, v109, v138
	v_fmac_f32_e32 v65, v135, v108
	v_fmac_f32_e32 v65, v136, v111
	v_fmac_f32_e32 v65, v137, v110
	ds_write2st64_b32 v145, v64, v65 offset0:16 offset1:24
	v_cvt_pk_bf16_f32 v64, v65, s0
	ds_write_b16 v163, v64 offset:35888
	v_fma_f32 v64, v134, v108, v138
	v_fmac_f32_e32 v64, v135, v111
	v_fmac_f32_e32 v64, v136, v110
	v_fmac_f32_e32 v64, v137, v113
	v_cvt_pk_bf16_f32 v65, v64, s0
	ds_write_b16 v163, v65 offset:36928
	v_fma_f32 v65, v134, v111, v138
	v_fmac_f32_e32 v65, v135, v110
	v_fmac_f32_e32 v65, v136, v113
	v_fmac_f32_e32 v65, v137, v112
	ds_write2st64_b32 v145, v64, v65 offset0:32 offset1:40
	v_cvt_pk_bf16_f32 v64, v65, s0
	ds_write_b16 v163, v64 offset:37968
	v_fma_f32 v64, v134, v110, v138
	v_fmac_f32_e32 v64, v135, v113
	v_fmac_f32_e32 v64, v136, v112
	v_fmac_f32_e32 v64, v137, v115
	v_cvt_pk_bf16_f32 v65, v64, s0
	ds_write_b16 v163, v65 offset:39008
	v_fma_f32 v65, v134, v113, v138
	v_fmac_f32_e32 v65, v135, v112
	v_fmac_f32_e32 v65, v136, v115
	v_fmac_f32_e32 v65, v137, v114
	ds_write2st64_b32 v145, v64, v65 offset0:48 offset1:56
	v_cvt_pk_bf16_f32 v64, v65, s0
	ds_write_b16 v163, v64 offset:40048
	v_fma_f32 v64, v134, v112, v138
	v_fmac_f32_e32 v64, v135, v115
	v_fmac_f32_e32 v64, v136, v114
	v_fmac_f32_e32 v64, v137, v117
	v_cvt_pk_bf16_f32 v65, v64, s0
	ds_write_b16 v163, v65 offset:41088
	v_fma_f32 v65, v134, v115, v138
	v_fmac_f32_e32 v65, v135, v114
	v_fmac_f32_e32 v65, v136, v117
	v_fmac_f32_e32 v65, v137, v116
	ds_write2st64_b32 v145, v64, v65 offset0:64 offset1:72
	v_cvt_pk_bf16_f32 v64, v65, s0
	ds_write_b16 v163, v64 offset:42128
	v_fma_f32 v64, v134, v114, v138
	v_fmac_f32_e32 v64, v135, v117
	v_fmac_f32_e32 v64, v136, v116
	v_fmac_f32_e32 v64, v137, v119
	v_cvt_pk_bf16_f32 v65, v64, s0
	ds_write_b16 v163, v65 offset:43168
	v_fma_f32 v65, v134, v117, v138
	v_fmac_f32_e32 v65, v135, v116
	v_fmac_f32_e32 v65, v136, v119
	v_fmac_f32_e32 v65, v137, v118
	ds_write2st64_b32 v145, v64, v65 offset0:80 offset1:88
	v_cvt_pk_bf16_f32 v64, v65, s0
	ds_write_b16 v163, v64 offset:44208
	v_fma_f32 v64, v134, v116, v138
	v_fmac_f32_e32 v64, v135, v119
	v_fmac_f32_e32 v64, v136, v118
	v_fmac_f32_e32 v64, v137, v121
	v_cvt_pk_bf16_f32 v65, v64, s0
	ds_write_b16 v163, v65 offset:45248
	v_fma_f32 v65, v134, v119, v138
	v_fmac_f32_e32 v65, v135, v118
	v_fmac_f32_e32 v65, v136, v121
	v_fmac_f32_e32 v65, v137, v120
	ds_write2st64_b32 v145, v64, v65 offset0:96 offset1:104
	v_cvt_pk_bf16_f32 v64, v65, s0
	ds_write_b16 v163, v64 offset:46288
	v_fma_f32 v64, v134, v118, v138
	v_fmac_f32_e32 v64, v135, v121
	v_mov_b64_e32 v[106:107], v[122:123]
	v_fmac_f32_e32 v64, v136, v120
	v_fmac_f32_e32 v64, v137, v107
	v_cvt_pk_bf16_f32 v65, v64, s0
	ds_write_b16 v163, v65 offset:47328
	v_fma_f32 v65, v134, v121, v138
	v_fmac_f32_e32 v65, v135, v120
	v_fmac_f32_e32 v65, v136, v107
	v_fmac_f32_e32 v65, v137, v106
	v_mov_b32_e32 v139, v120
	ds_write2st64_b32 v145, v64, v65 offset0:112 offset1:120
	v_cvt_pk_bf16_f32 v64, v65, s0
	s_cmp_eq_u32 s10, 3
	s_mov_b32 s8, 48
	ds_write_b16 v163, v64 offset:48368
	s_cbranch_scc1 .LBB0_317
	s_lshl_b32 s8, s10, 4
	s_add_i32 s16, s11, s8
	s_ashr_i32 s17, s16, 31
	s_lshr_b64 s[18:19], s[16:17], 8
	v_mad_u64_u32 v[64:65], s[18:19], s18, 49, v[102:103]
	s_lshr_b32 s9, s17, 8
	v_mov_b32_e32 v66, v65
	v_mad_u64_u32 v[66:67], s[18:19], s9, 49, v[66:67]
	v_mov_b32_e32 v65, v66
	v_lshlrev_b64 v[64:65], 17, v[64:65]
	s_lshl_b32 s9, s16, 9
	v_lshl_add_u64 v[64:65], v[100:101], 0, v[64:65]
	s_and_b32 s96, s9, 0x1e000
	v_lshl_add_u64 v[64:65], v[64:65], 0, s[96:97]
	v_lshl_add_u64 v[64:65], v[166:167], 1, v[64:65]
	global_load_ushort v108, v[64:65], off offset:512
	global_load_ushort v110, v[64:65], off offset:1536
	global_load_ushort v112, v[64:65], off offset:2560
	global_load_ushort v114, v[64:65], off offset:3584
	global_load_ushort v115, v[64:65], off offset:3072
	global_load_ushort v113, v[64:65], off offset:2048
	global_load_ushort v111, v[64:65], off offset:1024
	global_load_ushort v109, v[64:65], off
	v_add_co_u32_e32 v64, vcc, s91, v64
	v_addc_co_u32_e32 v65, vcc, 0, v65, vcc
	global_load_ushort v117, v[64:65], off
	global_load_ushort v122, v[64:65], off offset:3584
	global_load_ushort v120, v[64:65], off offset:2560
	global_load_ushort v118, v[64:65], off offset:1536
	global_load_ushort v116, v[64:65], off offset:512
	global_load_ushort v119, v[64:65], off offset:1024
	global_load_ushort v121, v[64:65], off offset:2048
	s_nop 0
	global_load_ushort v123, v[64:65], off offset:3072
.LBB0_317:
	s_waitcnt lgkmcnt(0)
	s_barrier
	ds_read_b128 v[64:67], v164 offset:32768
	ds_read_b128 v[188:191], v164 offset:32832
	ds_read2_b32 v[124:125], v146 offset1:16
	s_add_i32 s8, s14, s8
	s_movk_i32 s16, 0x8000
	s_waitcnt lgkmcnt(2)
	v_mfma_f32_16x16x32_bf16 v[68:71], v[64:67], v[0:3], 0
	s_waitcnt lgkmcnt(1)
	v_mfma_f32_16x16x32_bf16 v[96:99], v[188:191], v[8:11], v[68:71]
	v_mfma_f32_16x16x32_bf16 v[72:75], v[64:67], v[4:7], 0
	v_mfma_f32_16x16x32_bf16 v[92:95], v[188:191], v[12:15], v[72:75]
	s_nop 5
	v_add_f32_e32 v96, v126, v96
	v_mul_f32_e32 v96, 0xbfb8aa3b, v96
	v_exp_f32_e32 v96, v96
	v_mfma_f32_16x16x32_bf16 v[76:79], v[64:67], v[16:19], 0
	v_add_f32_e32 v96, 1.0, v96
	v_rcp_f32_e32 v96, v96
	v_add_f32_e32 v92, v127, v92
	v_mul_f32_e32 v92, 0xbfb8aa3b, v92
	v_exp_f32_e32 v92, v92
	v_mul_f32_e32 v96, v140, v96
	v_mul_f32_e32 v96, 0xbfb8aa3b, v96
	v_exp_f32_e32 v169, v96
	v_add_f32_e32 v92, 1.0, v92
	v_rcp_f32_e32 v92, v92
	v_add_f32_e32 v93, v127, v93
	v_fma_f32 v96, -v169, v169, 1.0
	v_max_f32_e32 v96, 0, v96
	v_sqrt_f32_e32 v96, v96
	v_mul_f32_e32 v93, 0xbfb8aa3b, v93
	v_exp_f32_e32 v93, v93
	v_mfma_f32_16x16x32_bf16 v[88:91], v[188:191], v[24:27], v[76:79]
	v_mul_f32_e32 v92, v92, v96
	s_waitcnt lgkmcnt(0)
	v_mul_f32_e32 v92, v124, v92
	ds_write_b32 v147, v92
	v_add_f32_e32 v92, v126, v97
	v_mul_f32_e32 v92, 0xbfb8aa3b, v92
	v_exp_f32_e32 v92, v92
	v_add_f32_e32 v93, 1.0, v93
	v_add_u32_e32 v124, 0x800, v146
	v_rcp_f32_e32 v93, v93
	v_add_f32_e32 v92, 1.0, v92
	v_rcp_f32_e32 v92, v92
	ds_read2_b32 v[96:97], v124 offset1:16
	v_add_f32_e32 v88, v128, v88
	v_mul_f32_e32 v88, 0xbfb8aa3b, v88
	v_mul_f32_e32 v92, v140, v92
	v_mul_f32_e32 v92, 0xbfb8aa3b, v92
	v_exp_f32_e32 v170, v92
	v_exp_f32_e32 v88, v88
	v_mfma_f32_16x16x32_bf16 v[84:87], v[64:67], v[20:23], 0
	v_fma_f32 v92, -v170, v170, 1.0
	v_max_f32_e32 v92, 0, v92
	v_sqrt_f32_e32 v92, v92
	v_add_f32_e32 v88, 1.0, v88
	v_rcp_f32_e32 v88, v88
	v_mfma_f32_16x16x32_bf16 v[84:87], v[188:191], v[28:31], v[84:87]
	v_mul_f32_e32 v92, v93, v92
	s_waitcnt lgkmcnt(0)
	v_mul_f32_e32 v92, v96, v92
	ds_write_b32 v148, v92
	v_add_f32_e32 v92, v126, v98
	v_mul_f32_e32 v92, 0xbfb8aa3b, v92
	v_exp_f32_e32 v92, v92
	v_add_f32_e32 v93, v127, v94
	v_mul_f32_e32 v93, 0xbfb8aa3b, v93
	v_exp_f32_e32 v93, v93
	v_add_f32_e32 v92, 1.0, v92
	v_rcp_f32_e32 v92, v92
	v_add_u32_e32 v96, 0x1000, v146
	v_add_f32_e32 v93, 1.0, v93
	v_rcp_f32_e32 v93, v93
	v_mul_f32_e32 v92, v140, v92
	v_mul_f32_e32 v92, 0xbfb8aa3b, v92
	v_exp_f32_e32 v98, v92
	v_mul_f32_e32 v88, v142, v88
	v_add_f32_e32 v84, v129, v84
	v_mul_f32_e32 v88, 0xbfb8aa3b, v88
	v_fma_f32 v92, -v98, v98, 1.0
	v_max_f32_e32 v92, 0, v92
	v_sqrt_f32_e32 v92, v92
	v_mul_f32_e32 v84, 0xbfb8aa3b, v84
	v_exp_f32_e32 v88, v88
	v_exp_f32_e32 v84, v84
	v_mul_f32_e32 v94, v93, v92
	ds_read2_b32 v[92:93], v96 offset1:16
	v_add_f32_e32 v85, v129, v85
	v_add_f32_e32 v84, 1.0, v84
	v_rcp_f32_e32 v84, v84
	v_mul_f32_e32 v85, 0xbfb8aa3b, v85
	s_waitcnt lgkmcnt(0)
	v_mul_f32_e32 v92, v94, v92
	ds_write_b32 v149, v92
	v_add_f32_e32 v92, v126, v99
	v_mul_f32_e32 v92, 0xbfb8aa3b, v92
	v_exp_f32_e32 v92, v92
	v_add_f32_e32 v94, v127, v95
	v_mul_f32_e32 v94, 0xbfb8aa3b, v94
	v_exp_f32_e32 v94, v94
	v_add_f32_e32 v92, 1.0, v92
	v_rcp_f32_e32 v92, v92
	v_exp_f32_e32 v85, v85
	v_add_f32_e32 v94, 1.0, v94
	v_rcp_f32_e32 v94, v94
	v_mul_f32_e32 v92, v140, v92
	v_mul_f32_e32 v92, 0xbfb8aa3b, v92
	v_exp_f32_e32 v99, v92
	v_add_f32_e32 v85, 1.0, v85
	v_rcp_f32_e32 v85, v85
	v_mfma_f32_16x16x32_bf16 v[176:179], v[64:67], v[32:35], 0
	v_fma_f32 v92, -v99, v99, 1.0
	v_max_f32_e32 v92, 0, v92
	v_sqrt_f32_e32 v92, v92
	v_mfma_f32_16x16x32_bf16 v[76:79], v[188:191], v[40:43], v[176:179]
	v_mul_f32_e32 v171, v94, v92
	v_add_u32_e32 v92, 0x1800, v146
	ds_read2_b32 v[94:95], v92 offset1:16
	s_nop 4
	v_add_f32_e32 v76, v130, v76
	v_mul_f32_e32 v76, 0xbfb8aa3b, v76
	v_exp_f32_e32 v76, v76
	v_mfma_f32_16x16x32_bf16 v[180:183], v[64:67], v[36:39], 0
	s_waitcnt lgkmcnt(0)
	v_mul_f32_e32 v94, v171, v94
	ds_write_b32 v150, v94
	v_fma_f32 v94, -v88, v88, 1.0
	v_max_f32_e32 v94, 0, v94
	v_sqrt_f32_e32 v171, v94
	v_add_u32_e32 v94, 0xc000, v146
	ds_write2_b32 v94, v169, v88 offset0:64 offset1:80
	v_add_f32_e32 v76, 1.0, v76
	v_mul_f32_e32 v84, v84, v171
	v_mul_f32_e32 v84, v84, v125
	ds_write_b32 v151, v84
	v_add_f32_e32 v84, v128, v89
	v_mul_f32_e32 v84, 0xbfb8aa3b, v84
	v_exp_f32_e32 v84, v84
	v_add_u32_e32 v89, 0xc800, v146
	v_rcp_f32_e32 v76, v76
	v_mfma_f32_16x16x32_bf16 v[72:75], v[188:191], v[44:47], v[180:183]
	v_add_f32_e32 v84, 1.0, v84
	v_rcp_f32_e32 v84, v84
	v_mul_f32_e32 v76, v143, v76
	v_mul_f32_e32 v76, 0xbfb8aa3b, v76
	v_mfma_f32_16x16x32_bf16 v[184:187], v[64:67], v[48:51], 0
	v_mul_f32_e32 v84, v142, v84
	v_mul_f32_e32 v84, 0xbfb8aa3b, v84
	v_exp_f32_e32 v84, v84
	v_add_f32_e32 v72, v131, v72
	v_mul_f32_e32 v72, 0xbfb8aa3b, v72
	v_exp_f32_e32 v72, v72
	v_fma_f32 v88, -v84, v84, 1.0
	v_max_f32_e32 v88, 0, v88
	v_sqrt_f32_e32 v88, v88
	ds_write2_b32 v89, v170, v84 offset0:64 offset1:80
	v_add_f32_e32 v72, 1.0, v72
	v_rcp_f32_e32 v72, v72
	v_mul_f32_e32 v84, v85, v88
	v_mul_f32_e32 v84, v84, v97
	ds_write_b32 v152, v84
	v_add_f32_e32 v84, v128, v90
	v_mul_f32_e32 v84, 0xbfb8aa3b, v84
	v_exp_f32_e32 v84, v84
	v_add_f32_e32 v85, v129, v86
	v_mul_f32_e32 v85, 0xbfb8aa3b, v85
	v_exp_f32_e32 v85, v85
	v_add_f32_e32 v84, 1.0, v84
	v_rcp_f32_e32 v84, v84
	v_add_u32_e32 v90, 0xd000, v146
	v_add_f32_e32 v85, 1.0, v85
	v_rcp_f32_e32 v85, v85
	v_mul_f32_e32 v84, v142, v84
	v_mul_f32_e32 v84, 0xbfb8aa3b, v84
	v_exp_f32_e32 v84, v84
	v_add_u32_e32 v88, 0xd800, v146
	v_add_f32_e32 v73, v131, v73
	v_mul_f32_e32 v73, 0xbfb8aa3b, v73
	v_fma_f32 v86, -v84, v84, 1.0
	v_max_f32_e32 v86, 0, v86
	v_sqrt_f32_e32 v86, v86
	ds_write2_b32 v90, v98, v84 offset0:64 offset1:80
	v_exp_f32_e32 v73, v73
	v_mfma_f32_16x16x32_bf16 v[68:71], v[188:191], v[56:59], v[184:187]
	v_mul_f32_e32 v84, v85, v86
	v_mul_f32_e32 v84, v84, v93
	ds_write_b32 v153, v84
	v_add_f32_e32 v84, v128, v91
	v_mul_f32_e32 v84, 0xbfb8aa3b, v84
	v_exp_f32_e32 v84, v84
	v_add_f32_e32 v85, v129, v87
	v_mul_f32_e32 v85, 0xbfb8aa3b, v85
	v_exp_f32_e32 v85, v85
	v_add_f32_e32 v84, 1.0, v84
	v_rcp_f32_e32 v84, v84
	v_exp_f32_e32 v91, v76
	v_add_f32_e32 v85, 1.0, v85
	v_rcp_f32_e32 v85, v85
	v_mul_f32_e32 v84, v142, v84
	v_mul_f32_e32 v84, 0xbfb8aa3b, v84
	v_exp_f32_e32 v84, v84
	v_fma_f32 v76, -v91, v91, 1.0
	v_max_f32_e32 v76, 0, v76
	v_sqrt_f32_e32 v76, v76
	v_fma_f32 v86, -v84, v84, 1.0
	v_max_f32_e32 v86, 0, v86
	v_sqrt_f32_e32 v86, v86
	ds_write2_b32 v88, v99, v84 offset0:64 offset1:80
	v_mul_f32_e32 v72, v72, v76
	v_add_f32_e32 v73, 1.0, v73
	v_mul_f32_e32 v84, v85, v86
	v_mul_f32_e32 v84, v84, v95
	ds_write_b32 v154, v84
	ds_read2_b32 v[84:85], v146 offset0:32 offset1:48
	v_rcp_f32_e32 v73, v73
	ds_read2_b32 v[86:87], v96 offset0:32 offset1:48
	v_add_f32_e32 v68, v132, v68
	v_mul_f32_e32 v68, 0xbfb8aa3b, v68
	s_waitcnt lgkmcnt(1)
	v_mul_f32_e32 v72, v72, v84
	ds_write_b32 v155, v72
	v_add_f32_e32 v72, v130, v77
	v_mul_f32_e32 v72, 0xbfb8aa3b, v72
	v_exp_f32_e32 v72, v72
	ds_read2_b32 v[76:77], v124 offset0:32 offset1:48
	v_exp_f32_e32 v68, v68
	v_mfma_f32_16x16x32_bf16 v[64:67], v[64:67], v[52:55], 0
	v_add_f32_e32 v72, 1.0, v72
	v_rcp_f32_e32 v72, v72
	v_add_f32_e32 v68, 1.0, v68
	v_rcp_f32_e32 v68, v68
	v_mfma_f32_16x16x32_bf16 v[64:67], v[188:191], v[60:63], v[64:67]
	v_mul_f32_e32 v72, v143, v72
	v_mul_f32_e32 v72, 0xbfb8aa3b, v72
	v_exp_f32_e32 v84, v72
	v_mul_f32_e32 v68, v144, v68
	v_mul_f32_e32 v68, 0xbfb8aa3b, v68
	s_nop 2
	v_add_f32_e32 v64, v133, v64
	v_fma_f32 v72, -v84, v84, 1.0
	v_max_f32_e32 v72, 0, v72
	v_sqrt_f32_e32 v72, v72
	v_mul_f32_e32 v64, 0xbfb8aa3b, v64
	v_exp_f32_e32 v68, v68
	v_exp_f32_e32 v64, v64
	v_mul_f32_e32 v72, v73, v72
	s_waitcnt lgkmcnt(0)
	v_mul_f32_e32 v72, v72, v76
	ds_write_b32 v156, v72
	v_add_f32_e32 v72, v130, v78
	v_mul_f32_e32 v72, 0xbfb8aa3b, v72
	v_exp_f32_e32 v72, v72
	v_add_f32_e32 v73, v131, v74
	v_mul_f32_e32 v73, 0xbfb8aa3b, v73
	v_exp_f32_e32 v73, v73
	v_add_f32_e32 v72, 1.0, v72
	v_rcp_f32_e32 v72, v72
	v_add_f32_e32 v64, 1.0, v64
	v_add_f32_e32 v73, 1.0, v73
	v_rcp_f32_e32 v73, v73
	v_mul_f32_e32 v72, v143, v72
	v_mul_f32_e32 v72, 0xbfb8aa3b, v72
	v_exp_f32_e32 v74, v72
	v_rcp_f32_e32 v64, v64
	v_add_f32_e32 v65, v133, v65
	v_mul_f32_e32 v65, 0xbfb8aa3b, v65
	v_fma_f32 v72, -v74, v74, 1.0
	v_max_f32_e32 v72, 0, v72
	v_sqrt_f32_e32 v72, v72
	v_exp_f32_e32 v65, v65
	ds_write2_b32 v94, v91, v68 offset0:96 offset1:112
	v_mul_f32_e32 v72, v73, v72
	v_mul_f32_e32 v72, v72, v86
	ds_write_b32 v157, v72
	v_add_f32_e32 v72, v130, v79
	v_mul_f32_e32 v72, 0xbfb8aa3b, v72
	v_exp_f32_e32 v72, v72
	v_add_f32_e32 v73, v131, v75
	v_mul_f32_e32 v73, 0xbfb8aa3b, v73
	v_exp_f32_e32 v73, v73
	v_add_f32_e32 v72, 1.0, v72
	v_rcp_f32_e32 v72, v72
	v_add_f32_e32 v65, 1.0, v65
	v_add_f32_e32 v73, 1.0, v73
	v_rcp_f32_e32 v73, v73
	v_mul_f32_e32 v72, v143, v72
	v_mul_f32_e32 v72, 0xbfb8aa3b, v72
	v_exp_f32_e32 v75, v72
	v_rcp_f32_e32 v65, v65
	v_fma_f32 v72, -v75, v75, 1.0
	v_max_f32_e32 v72, 0, v72
	v_sqrt_f32_e32 v72, v72
	s_nop 0
	v_mul_f32_e32 v76, v73, v72
	ds_read2_b32 v[72:73], v92 offset0:32 offset1:48
	s_waitcnt lgkmcnt(0)
	v_mul_f32_e32 v72, v76, v72
	ds_write_b32 v158, v72
	v_fma_f32 v72, -v68, v68, 1.0
	v_max_f32_e32 v72, 0, v72
	v_sqrt_f32_e32 v72, v72
	s_nop 0
	v_mul_f32_e32 v64, v64, v72
	v_mul_f32_e32 v64, v64, v85
	ds_write_b32 v159, v64
	v_add_f32_e32 v64, v132, v69
	v_mul_f32_e32 v64, 0xbfb8aa3b, v64
	v_exp_f32_e32 v64, v64
	s_nop 0
	v_add_f32_e32 v64, 1.0, v64
	v_rcp_f32_e32 v64, v64
	s_nop 0
	v_mul_f32_e32 v64, v144, v64
	v_mul_f32_e32 v64, 0xbfb8aa3b, v64
	v_exp_f32_e32 v64, v64
	ds_write2_b32 v89, v84, v64 offset0:96 offset1:112
	v_fma_f32 v68, -v64, v64, 1.0
	v_max_f32_e32 v68, 0, v68
	v_sqrt_f32_e32 v68, v68
	s_nop 0
	v_mul_f32_e32 v64, v65, v68
	v_mul_f32_e32 v64, v64, v77
	ds_write_b32 v160, v64
	v_add_f32_e32 v64, v132, v70
	v_mul_f32_e32 v64, 0xbfb8aa3b, v64
	v_exp_f32_e32 v64, v64
	v_add_f32_e32 v65, v133, v66
	v_mul_f32_e32 v65, 0xbfb8aa3b, v65
	v_exp_f32_e32 v65, v65
	v_add_f32_e32 v64, 1.0, v64
	v_rcp_f32_e32 v64, v64
	v_add_f32_e32 v65, 1.0, v65
	v_rcp_f32_e32 v65, v65
	v_mul_f32_e32 v64, v144, v64
	v_mul_f32_e32 v64, 0xbfb8aa3b, v64
	v_exp_f32_e32 v64, v64
	ds_write2_b32 v90, v74, v64 offset0:96 offset1:112
	v_fma_f32 v66, -v64, v64, 1.0
	v_max_f32_e32 v66, 0, v66
	v_sqrt_f32_e32 v66, v66
	s_nop 0
	v_mul_f32_e32 v64, v65, v66
	v_mul_f32_e32 v64, v64, v87
	ds_write_b32 v161, v64
	v_add_f32_e32 v64, v132, v71
	v_mul_f32_e32 v64, 0xbfb8aa3b, v64
	v_exp_f32_e32 v64, v64
	v_add_f32_e32 v65, v133, v67
	v_mul_f32_e32 v65, 0xbfb8aa3b, v65
	v_exp_f32_e32 v65, v65
	v_add_f32_e32 v64, 1.0, v64
	v_rcp_f32_e32 v64, v64
	v_add_f32_e32 v65, 1.0, v65
	v_rcp_f32_e32 v65, v65
	v_mul_f32_e32 v64, v144, v64
	v_mul_f32_e32 v64, 0xbfb8aa3b, v64
	v_exp_f32_e32 v64, v64
	ds_write2_b32 v88, v75, v64 offset0:96 offset1:112
	v_fma_f32 v66, -v64, v64, 1.0
	v_max_f32_e32 v66, 0, v66
	v_sqrt_f32_e32 v66, v66
	s_nop 0
	v_mul_f32_e32 v64, v65, v66
	v_mul_f32_e32 v64, v64, v73
	ds_write_b32 v162, v64
	s_waitcnt lgkmcnt(0)
	s_cmp_eq_u32 s10, 3
	s_cbranch_scc1 .Llru_nx_skip
	s_waitcnt vmcnt(0)
	v_lshlrev_b32_e32 v108, 16, v108
	v_lshlrev_b32_e32 v109, 16, v109
	v_lshlrev_b32_e32 v110, 16, v110
	v_lshlrev_b32_e32 v111, 16, v111
	v_lshlrev_b32_e32 v112, 16, v112
	v_lshlrev_b32_e32 v113, 16, v113
	v_lshlrev_b32_e32 v114, 16, v114
	v_lshlrev_b32_e32 v115, 16, v115
	v_lshlrev_b32_e32 v116, 16, v116
	v_lshlrev_b32_e32 v117, 16, v117
	v_lshlrev_b32_e32 v118, 16, v118
	v_lshlrev_b32_e32 v119, 16, v119
	v_lshlrev_b32_e32 v120, 16, v120
	v_lshlrev_b32_e32 v121, 16, v121
	v_lshlrev_b32_e32 v122, 16, v122
	v_lshlrev_b32_e32 v123, 16, v123
.Llru_nx_skip:
	s_barrier
.LBB0_318:
	v_add_u32_e32 v66, s16, v145
	v_add_u32_e32 v64, 0x14100, v66
	v_add_u32_e32 v65, 0x1c100, v66
	ds_read_b32 v64, v64
	ds_read_b32 v67, v65
	s_ashr_i32 s9, s8, 31
	s_lshl_b64 s[18:19], s[8:9], 11
	s_addk_i32 s16, 0x2000
	s_waitcnt lgkmcnt(1)
	v_mul_f32_e32 v68, v165, v64
	s_waitcnt lgkmcnt(0)
	v_fmac_f32_e32 v67, v141, v64
	v_cvt_pk_bf16_f32 v69, v67, v68
	v_lshl_add_u64 v[64:65], v[104:105], 0, s[18:19]
	global_store_dword v[64:65], v69, off
	v_add_u32_e32 v64, 0x14900, v66
	v_add_u32_e32 v65, 0x1c900, v66
	ds_read_b32 v64, v64
	ds_read_b32 v69, v65
	s_add_i32 s18, s8, 1
	s_ashr_i32 s19, s18, 31
	s_lshl_b64 s[18:19], s[18:19], 11
	s_waitcnt lgkmcnt(0)
	v_fmac_f32_e32 v69, v67, v64
	v_mul_f32_e32 v67, v68, v64
	v_cvt_pk_bf16_f32 v68, v69, v67
	v_lshl_add_u64 v[64:65], v[104:105], 0, s[18:19]
	global_store_dword v[64:65], v68, off
	v_add_u32_e32 v64, 0x15100, v66
	v_add_u32_e32 v65, 0x1d100, v66
	ds_read_b32 v64, v64
	ds_read_b32 v68, v65
	s_add_i32 s18, s8, 2
	s_ashr_i32 s19, s18, 31
	s_lshl_b64 s[18:19], s[18:19], 11
	s_waitcnt lgkmcnt(1)
	v_mul_f32_e32 v67, v67, v64
	s_waitcnt lgkmcnt(0)
	v_fmac_f32_e32 v68, v69, v64
	v_cvt_pk_bf16_f32 v69, v68, v67
	v_lshl_add_u64 v[64:65], v[104:105], 0, s[18:19]
	global_store_dword v[64:65], v69, off
	v_add_u32_e32 v64, 0x15900, v66
	v_add_u32_e32 v65, 0x1d900, v66
	ds_read_b32 v64, v64
	ds_read_b32 v141, v65
	s_add_i32 s18, s8, 3
	s_ashr_i32 s19, s18, 31
	s_lshl_b64 s[18:19], s[18:19], 11
	s_waitcnt lgkmcnt(1)
	v_mul_f32_e32 v165, v67, v64
	s_waitcnt lgkmcnt(0)
	v_fmac_f32_e32 v141, v68, v64
	s_add_i32 s8, s8, 4
	v_cvt_pk_bf16_f32 v66, v141, v165
	v_lshl_add_u64 v[64:65], v[104:105], 0, s[18:19]
	s_cmp_eq_u32 s16, 0
	global_store_dword v[64:65], v66, off
	s_cbranch_scc0 .LBB0_318
	s_add_i32 s10, s10, 1
	s_cmp_eq_u32 s10, 4
	v_mov_b64_e32 v[68:69], v[106:107]
	s_cbranch_scc0 .LBB0_315
	s_add_i32 s15, s15, s66
	s_add_i32 s14, s14, s0
	s_cmpk_gt_i32 s15, 0xff
	s_barrier
	s_cbranch_scc0 .LBB0_311
	s_branch .LBB0_322
